# FFN-in GEMM: epilogue conv-weight loads issued before the closing wave-half rendezvous barrier
# baseline (speedup 1.0000x reference)
.Lgp_866:
.LBB0_866:
	ds_read_b128 v[64:67], v203
	ds_read_b128 v[68:71], v203 offset:1024
	ds_read_b128 v[72:75], v203 offset:2048
	ds_read_b128 v[76:79], v203 offset:3072
	ds_read_b128 v[80:83], v204
	ds_read_b128 v[84:87], v204 offset:1024
	ds_read_b128 v[88:91], v204 offset:2048
	ds_read_b128 v[92:95], v204 offset:3072
	s_add_u32 s64, s62, 0xfffc0080
	s_addc_u32 s65, s63, -1
	s_cmp_eq_u32 s90, 12
	s_cselect_b32 s67, s55, s65
	s_cselect_b32 s66, s86, s64
	s_cselect_b32 s65, s53, s89
	s_cselect_b32 s64, s87, s88
	v_lshl_add_u64 v[220:221], s[62:63], 0, v[172:173]
	s_add_i32 m0, s73, 0xc000
	ds_read_b128 v[180:183], v205
	ds_read_b128 v[184:187], v205 offset:1024
	ds_read_b128 v[188:191], v205 offset:2048
	ds_read_b128 v[192:195], v205 offset:3072
	ds_read_b128 v[196:199], v205 offset:4096
	ds_read_b128 v[208:211], v205 offset:5120
	ds_read_b128 v[212:215], v205 offset:6144
	ds_read_b128 v[216:219], v205 offset:7168
	global_load_lds_dwordx4 v[220:221], off
	v_lshl_add_u64 v[220:221], s[62:63], 0, v[174:175]
	s_add_i32 m0, s73, 0xe000
	s_nop 0
	global_load_lds_dwordx4 v[220:221], off
	s_waitcnt vmcnt(8)
	s_waitcnt lgkmcnt(0)
	s_barrier
	s_waitcnt lgkmcnt(0)
	v_mfma_f32_16x16x32_bf16 v[148:151], v[64:67], v[180:183], v[148:151]
	v_mfma_f32_16x16x32_bf16 v[144:147], v[72:75], v[180:183], v[144:147]
	v_mfma_f32_16x16x32_bf16 v[132:135], v[64:67], v[188:191], v[132:135]
	v_mfma_f32_16x16x32_bf16 v[128:131], v[72:75], v[188:191], v[128:131]
	v_mfma_f32_16x16x32_bf16 v[116:119], v[64:67], v[196:199], v[116:119]
	v_mfma_f32_16x16x32_bf16 v[112:115], v[72:75], v[196:199], v[112:115]
	v_mfma_f32_16x16x32_bf16 v[104:107], v[64:67], v[212:215], v[104:107]
	v_mfma_f32_16x16x32_bf16 v[100:103], v[72:75], v[212:215], v[100:103]
	v_mfma_f32_16x16x32_bf16 v[148:151], v[68:71], v[184:187], v[148:151]
	v_mfma_f32_16x16x32_bf16 v[144:147], v[76:79], v[184:187], v[144:147]
	v_mfma_f32_16x16x32_bf16 v[132:135], v[68:71], v[192:195], v[132:135]
	v_mfma_f32_16x16x32_bf16 v[128:131], v[76:79], v[192:195], v[128:131]
	v_mfma_f32_16x16x32_bf16 v[116:119], v[68:71], v[208:211], v[116:119]
	v_mfma_f32_16x16x32_bf16 v[112:115], v[76:79], v[208:211], v[112:115]
	v_mfma_f32_16x16x32_bf16 v[104:107], v[68:71], v[216:219], v[104:107]
	v_mfma_f32_16x16x32_bf16 v[100:103], v[76:79], v[216:219], v[100:103]
	v_mfma_f32_16x16x32_bf16 v[152:155], v[80:83], v[180:183], v[152:155]
	v_mfma_f32_16x16x32_bf16 v[156:159], v[88:91], v[180:183], v[156:159]
	v_mfma_f32_16x16x32_bf16 v[136:139], v[80:83], v[188:191], v[136:139]
	v_mfma_f32_16x16x32_bf16 v[140:143], v[88:91], v[188:191], v[140:143]
	v_mfma_f32_16x16x32_bf16 v[120:123], v[80:83], v[196:199], v[120:123]
	v_mfma_f32_16x16x32_bf16 v[124:127], v[88:91], v[196:199], v[124:127]
	v_mfma_f32_16x16x32_bf16 v[96:99], v[80:83], v[212:215], v[96:99]
	v_mfma_f32_16x16x32_bf16 v[108:111], v[88:91], v[212:215], v[108:111]
	v_mfma_f32_16x16x32_bf16 v[152:155], v[84:87], v[184:187], v[152:155]
	v_mfma_f32_16x16x32_bf16 v[156:159], v[92:95], v[184:187], v[156:159]
	v_mfma_f32_16x16x32_bf16 v[136:139], v[84:87], v[192:195], v[136:139]
	v_mfma_f32_16x16x32_bf16 v[140:143], v[92:95], v[192:195], v[140:143]
	v_mfma_f32_16x16x32_bf16 v[120:123], v[84:87], v[208:211], v[120:123]
	v_mfma_f32_16x16x32_bf16 v[124:127], v[92:95], v[208:211], v[124:127]
	v_mfma_f32_16x16x32_bf16 v[96:99], v[84:87], v[216:219], v[96:99]
	v_mfma_f32_16x16x32_bf16 v[108:111], v[92:95], v[216:219], v[108:111]
	s_barrier
	s_add_i32 s91, s82, s72
	v_lshl_add_u64 v[220:221], s[64:65], 0, v[164:165]
	s_mov_b32 m0, s91
	ds_read_b128 v[180:183], v205 offset:16384
	ds_read_b128 v[184:187], v205 offset:17408
	ds_read_b128 v[188:191], v205 offset:18432
	ds_read_b128 v[192:195], v205 offset:19456
	ds_read_b128 v[196:199], v205 offset:20480
	ds_read_b128 v[208:211], v205 offset:21504
	ds_read_b128 v[212:215], v205 offset:22528
	ds_read_b128 v[216:219], v205 offset:23552
	global_load_lds_dwordx4 v[220:221], off
	s_add_i32 m0, s91, 0x2000
	s_add_u32 s92, s64, 0x40000
	v_lshl_add_u64 v[222:223], s[64:65], 0, v[160:161]
	s_addc_u32 s93, s65, 0
	s_add_i32 s91, s83, s72
	global_load_lds_dwordx4 v[222:223], off
	v_lshl_add_u64 v[224:225], s[92:93], 0, v[164:165]
	s_mov_b32 m0, s91
	v_lshl_add_u64 v[226:227], s[66:67], 0, v[162:163]
	global_load_lds_dwordx4 v[224:225], off
	v_lshl_add_u64 v[224:225], s[92:93], 0, v[160:161]
	s_add_i32 m0, s91, 0x2000
	s_nop 0
	global_load_lds_dwordx4 v[224:225], off
	v_lshl_add_u64 v[224:225], s[66:67], 0, v[166:167]
	s_mov_b32 m0, s73
	s_nop 0
	global_load_lds_dwordx4 v[224:225], off
	s_mov_b32 m0, s74
	s_nop 0
	global_load_lds_dwordx4 v[226:227], off
	s_waitcnt vmcnt(8)
	s_waitcnt lgkmcnt(0)
	s_barrier
	s_waitcnt lgkmcnt(0)
	v_mfma_f32_16x16x32_bf16 v[52:55], v[64:67], v[180:183], v[52:55]
	v_mfma_f32_16x16x32_bf16 v[48:51], v[72:75], v[180:183], v[48:51]
	v_mfma_f32_16x16x32_bf16 v[36:39], v[64:67], v[188:191], v[36:39]
	v_mfma_f32_16x16x32_bf16 v[32:35], v[72:75], v[188:191], v[32:35]
	v_mfma_f32_16x16x32_bf16 v[20:23], v[64:67], v[196:199], v[20:23]
	v_mfma_f32_16x16x32_bf16 v[16:19], v[72:75], v[196:199], v[16:19]
	v_mfma_f32_16x16x32_bf16 v[8:11], v[64:67], v[212:215], v[8:11]
	v_mfma_f32_16x16x32_bf16 v[4:7], v[72:75], v[212:215], v[4:7]
	v_mfma_f32_16x16x32_bf16 v[52:55], v[68:71], v[184:187], v[52:55]
	v_mfma_f32_16x16x32_bf16 v[48:51], v[76:79], v[184:187], v[48:51]
	v_mfma_f32_16x16x32_bf16 v[36:39], v[68:71], v[192:195], v[36:39]
	v_mfma_f32_16x16x32_bf16 v[32:35], v[76:79], v[192:195], v[32:35]
	v_mfma_f32_16x16x32_bf16 v[20:23], v[68:71], v[208:211], v[20:23]
	v_mfma_f32_16x16x32_bf16 v[16:19], v[76:79], v[208:211], v[16:19]
	v_mfma_f32_16x16x32_bf16 v[8:11], v[68:71], v[216:219], v[8:11]
	v_mfma_f32_16x16x32_bf16 v[4:7], v[76:79], v[216:219], v[4:7]
	v_mfma_f32_16x16x32_bf16 v[56:59], v[80:83], v[180:183], v[56:59]
	v_mfma_f32_16x16x32_bf16 v[60:63], v[88:91], v[180:183], v[60:63]
	v_mfma_f32_16x16x32_bf16 v[40:43], v[80:83], v[188:191], v[40:43]
	v_mfma_f32_16x16x32_bf16 v[44:47], v[88:91], v[188:191], v[44:47]
	v_mfma_f32_16x16x32_bf16 v[24:27], v[80:83], v[196:199], v[24:27]
	v_mfma_f32_16x16x32_bf16 v[28:31], v[88:91], v[196:199], v[28:31]
	v_mfma_f32_16x16x32_bf16 v[0:3], v[80:83], v[212:215], v[0:3]
	v_mfma_f32_16x16x32_bf16 v[12:15], v[88:91], v[212:215], v[12:15]
	v_mfma_f32_16x16x32_bf16 v[56:59], v[84:87], v[184:187], v[56:59]
	v_mfma_f32_16x16x32_bf16 v[60:63], v[92:95], v[184:187], v[60:63]
	v_mfma_f32_16x16x32_bf16 v[40:43], v[84:87], v[192:195], v[40:43]
	v_mfma_f32_16x16x32_bf16 v[44:47], v[92:95], v[192:195], v[44:47]
	v_mfma_f32_16x16x32_bf16 v[24:27], v[84:87], v[208:211], v[24:27]
	v_mfma_f32_16x16x32_bf16 v[28:31], v[92:95], v[208:211], v[28:31]
	v_mfma_f32_16x16x32_bf16 v[0:3], v[84:87], v[216:219], v[0:3]
	v_mfma_f32_16x16x32_bf16 v[12:15], v[92:95], v[216:219], v[12:15]
	s_barrier
	s_add_i32 s91, 0, 0x18000
	s_add_i32 s92, 0, 0x1c000
	v_add_u32_e32 v76, s91, v201
	v_add_u32_e32 v92, s92, v201
	ds_read_b128 v[64:67], v76
	ds_read_b128 v[68:71], v76 offset:1024
	ds_read_b128 v[72:75], v76 offset:2048
	ds_read_b128 v[76:79], v76 offset:3072
	ds_read_b128 v[80:83], v92
	ds_read_b128 v[84:87], v92 offset:1024
	ds_read_b128 v[88:91], v92 offset:2048
	ds_read_b128 v[92:95], v92 offset:3072
	s_add_u32 s66, s66, 0x40000
	s_addc_u32 s67, s67, 0
	s_mov_b32 m0, s75
	v_lshl_add_u64 v[228:229], s[66:67], 0, v[166:167]
	ds_read_b128 v[180:183], v205 offset:32768
	ds_read_b128 v[184:187], v205 offset:33792
	ds_read_b128 v[188:191], v205 offset:34816
	ds_read_b128 v[192:195], v205 offset:35840
	ds_read_b128 v[196:199], v205 offset:36864
	ds_read_b128 v[208:211], v205 offset:37888
	ds_read_b128 v[212:215], v205 offset:38912
	ds_read_b128 v[216:219], v205 offset:39936
	global_load_lds_dwordx4 v[228:229], off
	v_lshl_add_u64 v[228:229], s[66:67], 0, v[162:163]
	s_mov_b32 m0, s76
	s_nop 0
	global_load_lds_dwordx4 v[228:229], off
	s_waitcnt vmcnt(8)
	s_waitcnt lgkmcnt(0)
	s_barrier
	s_waitcnt lgkmcnt(0)
	v_mfma_f32_16x16x32_bf16 v[148:151], v[64:67], v[180:183], v[148:151]
	v_mfma_f32_16x16x32_bf16 v[144:147], v[72:75], v[180:183], v[144:147]
	v_mfma_f32_16x16x32_bf16 v[132:135], v[64:67], v[188:191], v[132:135]
	v_mfma_f32_16x16x32_bf16 v[128:131], v[72:75], v[188:191], v[128:131]
	v_mfma_f32_16x16x32_bf16 v[116:119], v[64:67], v[196:199], v[116:119]
	v_mfma_f32_16x16x32_bf16 v[112:115], v[72:75], v[196:199], v[112:115]
	v_mfma_f32_16x16x32_bf16 v[104:107], v[64:67], v[212:215], v[104:107]
	v_mfma_f32_16x16x32_bf16 v[100:103], v[72:75], v[212:215], v[100:103]
	v_mfma_f32_16x16x32_bf16 v[148:151], v[68:71], v[184:187], v[148:151]
	v_mfma_f32_16x16x32_bf16 v[144:147], v[76:79], v[184:187], v[144:147]
	v_mfma_f32_16x16x32_bf16 v[132:135], v[68:71], v[192:195], v[132:135]
	v_mfma_f32_16x16x32_bf16 v[128:131], v[76:79], v[192:195], v[128:131]
	v_mfma_f32_16x16x32_bf16 v[116:119], v[68:71], v[208:211], v[116:119]
	v_mfma_f32_16x16x32_bf16 v[112:115], v[76:79], v[208:211], v[112:115]
	v_mfma_f32_16x16x32_bf16 v[104:107], v[68:71], v[216:219], v[104:107]
	v_mfma_f32_16x16x32_bf16 v[100:103], v[76:79], v[216:219], v[100:103]
	v_mfma_f32_16x16x32_bf16 v[152:155], v[80:83], v[180:183], v[152:155]
	v_mfma_f32_16x16x32_bf16 v[156:159], v[88:91], v[180:183], v[156:159]
	v_mfma_f32_16x16x32_bf16 v[136:139], v[80:83], v[188:191], v[136:139]
	v_mfma_f32_16x16x32_bf16 v[140:143], v[88:91], v[188:191], v[140:143]
	v_mfma_f32_16x16x32_bf16 v[120:123], v[80:83], v[196:199], v[120:123]
	v_mfma_f32_16x16x32_bf16 v[124:127], v[88:91], v[196:199], v[124:127]
	v_mfma_f32_16x16x32_bf16 v[96:99], v[80:83], v[212:215], v[96:99]
	v_mfma_f32_16x16x32_bf16 v[108:111], v[88:91], v[212:215], v[108:111]
	v_mfma_f32_16x16x32_bf16 v[152:155], v[84:87], v[184:187], v[152:155]
	v_mfma_f32_16x16x32_bf16 v[156:159], v[92:95], v[184:187], v[156:159]
	v_mfma_f32_16x16x32_bf16 v[136:139], v[84:87], v[192:195], v[136:139]
	v_mfma_f32_16x16x32_bf16 v[140:143], v[92:95], v[192:195], v[140:143]
	v_mfma_f32_16x16x32_bf16 v[120:123], v[84:87], v[208:211], v[120:123]
	v_mfma_f32_16x16x32_bf16 v[124:127], v[92:95], v[208:211], v[124:127]
	v_mfma_f32_16x16x32_bf16 v[96:99], v[84:87], v[216:219], v[96:99]
	v_mfma_f32_16x16x32_bf16 v[108:111], v[92:95], v[216:219], v[108:111]
	s_barrier
	s_add_i32 s66, s91, s72
	v_lshl_add_u64 v[220:221], v[220:221], 0, s[20:21]
	s_mov_b32 m0, s66
	ds_read_b128 v[180:183], v205 offset:49152
	ds_read_b128 v[184:187], v205 offset:50176
	ds_read_b128 v[188:191], v205 offset:51200
	ds_read_b128 v[192:195], v205 offset:52224
	ds_read_b128 v[196:199], v205 offset:53248
	ds_read_b128 v[208:211], v205 offset:54272
	ds_read_b128 v[212:215], v205 offset:55296
	ds_read_b128 v[216:219], v205 offset:56320
	global_load_lds_dwordx4 v[220:221], off
	s_add_i32 m0, s66, 0x2000
	s_add_u32 s64, s64, 0x40080
	v_lshl_add_u64 v[220:221], v[222:223], 0, s[20:21]
	s_addc_u32 s65, s65, 0
	s_add_i32 s66, s92, s72
	global_load_lds_dwordx4 v[220:221], off
	v_lshl_add_u64 v[220:221], s[64:65], 0, v[164:165]
	s_mov_b32 m0, s66
	s_nop 0
	global_load_lds_dwordx4 v[220:221], off
	v_lshl_add_u64 v[220:221], s[64:65], 0, v[160:161]
	s_add_i32 m0, s66, 0x2000
	s_nop 0
	global_load_lds_dwordx4 v[220:221], off
	v_lshl_add_u64 v[220:221], v[224:225], 0, s[20:21]
	s_mov_b32 m0, s78
	s_nop 0
	global_load_lds_dwordx4 v[220:221], off
	v_lshl_add_u64 v[220:221], v[226:227], 0, s[20:21]
	s_mov_b32 m0, s79
	s_nop 0
	global_load_lds_dwordx4 v[220:221], off
	s_waitcnt vmcnt(8)
	s_waitcnt lgkmcnt(0)
	s_barrier
	s_waitcnt lgkmcnt(0)
	v_mfma_f32_16x16x32_bf16 v[52:55], v[64:67], v[180:183], v[52:55]
	v_mfma_f32_16x16x32_bf16 v[48:51], v[72:75], v[180:183], v[48:51]
	v_mfma_f32_16x16x32_bf16 v[36:39], v[64:67], v[188:191], v[36:39]
	v_mfma_f32_16x16x32_bf16 v[32:35], v[72:75], v[188:191], v[32:35]
	v_mfma_f32_16x16x32_bf16 v[20:23], v[64:67], v[196:199], v[20:23]
	v_mfma_f32_16x16x32_bf16 v[16:19], v[72:75], v[196:199], v[16:19]
	v_mfma_f32_16x16x32_bf16 v[8:11], v[64:67], v[212:215], v[8:11]
	v_mfma_f32_16x16x32_bf16 v[4:7], v[72:75], v[212:215], v[4:7]
	v_mfma_f32_16x16x32_bf16 v[52:55], v[68:71], v[184:187], v[52:55]
	v_mfma_f32_16x16x32_bf16 v[48:51], v[76:79], v[184:187], v[48:51]
	v_mfma_f32_16x16x32_bf16 v[36:39], v[68:71], v[192:195], v[36:39]
	v_mfma_f32_16x16x32_bf16 v[32:35], v[76:79], v[192:195], v[32:35]
	v_mfma_f32_16x16x32_bf16 v[20:23], v[68:71], v[208:211], v[20:23]
	v_mfma_f32_16x16x32_bf16 v[16:19], v[76:79], v[208:211], v[16:19]
	v_mfma_f32_16x16x32_bf16 v[8:11], v[68:71], v[216:219], v[8:11]
	v_mfma_f32_16x16x32_bf16 v[4:7], v[76:79], v[216:219], v[4:7]
	v_mfma_f32_16x16x32_bf16 v[56:59], v[80:83], v[180:183], v[56:59]
	v_mfma_f32_16x16x32_bf16 v[60:63], v[88:91], v[180:183], v[60:63]
	v_mfma_f32_16x16x32_bf16 v[40:43], v[80:83], v[188:191], v[40:43]
	v_mfma_f32_16x16x32_bf16 v[44:47], v[88:91], v[188:191], v[44:47]
	v_mfma_f32_16x16x32_bf16 v[24:27], v[80:83], v[196:199], v[24:27]
	v_mfma_f32_16x16x32_bf16 v[28:31], v[88:91], v[196:199], v[28:31]
	v_mfma_f32_16x16x32_bf16 v[0:3], v[80:83], v[212:215], v[0:3]
	v_mfma_f32_16x16x32_bf16 v[12:15], v[88:91], v[212:215], v[12:15]
	v_mfma_f32_16x16x32_bf16 v[56:59], v[84:87], v[184:187], v[56:59]
	v_mfma_f32_16x16x32_bf16 v[60:63], v[92:95], v[184:187], v[60:63]
	v_mfma_f32_16x16x32_bf16 v[40:43], v[84:87], v[192:195], v[40:43]
	v_mfma_f32_16x16x32_bf16 v[44:47], v[92:95], v[192:195], v[44:47]
	v_mfma_f32_16x16x32_bf16 v[24:27], v[84:87], v[208:211], v[24:27]
	v_mfma_f32_16x16x32_bf16 v[28:31], v[92:95], v[208:211], v[28:31]
	v_mfma_f32_16x16x32_bf16 v[0:3], v[84:87], v[216:219], v[0:3]
	v_mfma_f32_16x16x32_bf16 v[12:15], v[92:95], v[216:219], v[12:15]
	s_barrier
	s_add_i32 s90, s90, 2
	s_add_u32 s62, s62, 0x100
	s_addc_u32 s63, s63, 0
	s_add_u32 s88, s88, 0x100
	s_addc_u32 s89, s89, 0
	s_cmp_gt_u32 s90, 13
	s_cbranch_scc0 .LBB0_866
	s_setprio 0
	v_lshl_or_b32 v180, s1, 7, v202
	v_ashrrev_i32_e32 v181, 31, v180
	v_lshlrev_b64 v[190:191], 2, v[180:181]
	v_lshl_add_u64 v[68:69], s[46:47], 0, v[190:191]
	v_lshl_add_u64 v[70:71], s[44:45], 0, v[190:191]
	v_lshl_add_u64 v[72:73], s[50:51], 0, v[190:191]
	v_lshl_add_u64 v[84:85], s[48:49], 0, v[190:191]
	global_load_dwordx4 v[64:67], v[68:69], off
	global_load_dwordx4 v[80:83], v[68:69], off offset:16
	global_load_dwordx4 v[92:95], v[70:71], off offset:16
	global_load_dwordx4 v[76:79], v[70:71], off
	global_load_dwordx4 v[88:91], v[72:73], off offset:16
	s_nop 0
	global_load_dwordx4 v[72:75], v[72:73], off
	s_nop 0
	global_load_dwordx4 v[68:71], v[84:85], off
	s_nop 0
	global_load_dwordx4 v[84:87], v[84:85], off offset:16
	s_and_b64 vcc, exec, s[34:35]
	s_cbranch_vccz .LBB0_869
	s_barrier
.LBB0_869:
	s_lshl_b32 s1, s0, 2
	s_add_i32 s62, s1, s71
	s_ashr_i32 s63, s62, 31
	v_mov_b32_dpp v183, v148 row_ror:1 row_mask:0xf bank_mask:0xf
	v_mov_b32_dpp v209, v148 row_ror:2 row_mask:0xf bank_mask:0xf
	v_mov_b32_dpp v185, v149 row_ror:1 row_mask:0xf bank_mask:0xf
	v_mov_b32_dpp v210, v149 row_ror:2 row_mask:0xf bank_mask:0xf
	v_mov_b32_dpp v187, v150 row_ror:1 row_mask:0xf bank_mask:0xf
	v_mov_b32_dpp v211, v150 row_ror:2 row_mask:0xf bank_mask:0xf
	v_mov_b32_dpp v189, v151 row_ror:1 row_mask:0xf bank_mask:0xf
	v_mov_b32_dpp v212, v151 row_ror:2 row_mask:0xf bank_mask:0xf
	v_mov_b32_dpp v193, v144 row_ror:1 row_mask:0xf bank_mask:0xf
	v_mov_b32_dpp v213, v144 row_ror:2 row_mask:0xf bank_mask:0xf
	v_mov_b32_dpp v195, v145 row_ror:1 row_mask:0xf bank_mask:0xf
	v_mov_b32_dpp v192, v145 row_ror:2 row_mask:0xf bank_mask:0xf
	v_mov_b32_dpp v197, v146 row_ror:1 row_mask:0xf bank_mask:0xf
	v_mov_b32_dpp v194, v146 row_ror:2 row_mask:0xf bank_mask:0xf
	v_mov_b32_dpp v199, v147 row_ror:1 row_mask:0xf bank_mask:0xf
	v_mov_b32_dpp v196, v147 row_ror:2 row_mask:0xf bank_mask:0xf
	s_lshl_b64 s[64:65], s[62:63], 1
	v_mov_b32_dpp v183, v148 row_shr:1 row_mask:0xf bank_mask:0xf
	v_mov_b32_dpp v209, v148 row_shr:2 row_mask:0xf bank_mask:0xf
	v_mov_b32_dpp v185, v149 row_shr:1 row_mask:0xf bank_mask:0xf
	v_mov_b32_dpp v210, v149 row_shr:2 row_mask:0xf bank_mask:0xf
	v_mov_b32_dpp v187, v150 row_shr:1 row_mask:0xf bank_mask:0xf
	v_mov_b32_dpp v211, v150 row_shr:2 row_mask:0xf bank_mask:0xf
	v_mov_b32_dpp v189, v151 row_shr:1 row_mask:0xf bank_mask:0xf
	v_mov_b32_dpp v212, v151 row_shr:2 row_mask:0xf bank_mask:0xf
	v_mov_b32_dpp v193, v144 row_shr:1 row_mask:0xf bank_mask:0xf
	v_mov_b32_dpp v213, v144 row_shr:2 row_mask:0xf bank_mask:0xf
	v_mov_b32_dpp v195, v145 row_shr:1 row_mask:0xf bank_mask:0xf
	v_mov_b32_dpp v192, v145 row_shr:2 row_mask:0xf bank_mask:0xf
	v_mov_b32_dpp v197, v146 row_shr:1 row_mask:0xf bank_mask:0xf
	v_mov_b32_dpp v194, v146 row_shr:2 row_mask:0xf bank_mask:0xf
	v_mov_b32_dpp v199, v147 row_shr:1 row_mask:0xf bank_mask:0xf
	v_mov_b32_dpp v196, v147 row_shr:2 row_mask:0xf bank_mask:0xf
	s_and_saveexec_b64 s[66:67], s[2:3]
	s_xor_b64 s[66:67], exec, s[66:67]
	s_cbranch_execz .LBB0_871
	v_or_b32_e32 v186, s64, v168
	v_mov_b64_e32 v[182:183], s[14:15]
	v_mov_b64_e32 v[184:185], s[18:19]
	v_mad_u64_u32 v[182:183], s[86:87], v186, s84, v[182:183]
	v_mad_u64_u32 v[184:185], s[86:87], v186, s84, v[184:185]
	v_mad_i32_i24 v183, s65, v207, v183
	v_mad_i32_i24 v185, s65, v207, v185
	v_lshl_add_u64 v[182:183], v[182:183], 0, v[190:191]
	v_lshl_add_u64 v[184:185], v[184:185], 0, v[190:191]
	global_store_dwordx4 v[182:183], v[148:151], off
	global_store_dwordx4 v[182:183], v[144:147], off offset:16
	global_store_dwordx4 v[184:185], v[152:155], off
	global_store_dwordx4 v[184:185], v[156:159], off offset:16
	s_waitcnt vmcnt(0)
	v_mov_b32_e32 v188, v91
	v_mov_b32_e32 v186, v89
	v_mov_b32_e32 v184, v75
	v_mov_b32_e32 v182, v73

.Lgp_1552:
.LBB0_1552:
	ds_read_b128 v[64:67], v203
	ds_read_b128 v[68:71], v203 offset:1024
	ds_read_b128 v[72:75], v203 offset:2048
	ds_read_b128 v[76:79], v203 offset:3072
	ds_read_b128 v[80:83], v204
	ds_read_b128 v[84:87], v204 offset:1024
	ds_read_b128 v[88:91], v204 offset:2048
	ds_read_b128 v[92:95], v204 offset:3072
	s_add_u32 s62, s60, 0xfffc0080
	s_addc_u32 s63, s61, -1
	s_cmp_eq_u32 s88, 12
	s_cselect_b32 s65, s55, s63
	s_cselect_b32 s64, s84, s62
	s_cselect_b32 s63, s53, s87
	s_cselect_b32 s62, s85, s86
	v_lshl_add_u64 v[220:221], s[60:61], 0, v[172:173]
	s_add_i32 m0, s71, 0xc000
	ds_read_b128 v[180:183], v205
	ds_read_b128 v[184:187], v205 offset:1024
	ds_read_b128 v[188:191], v205 offset:2048
	ds_read_b128 v[192:195], v205 offset:3072
	ds_read_b128 v[196:199], v205 offset:4096
	ds_read_b128 v[208:211], v205 offset:5120
	ds_read_b128 v[212:215], v205 offset:6144
	ds_read_b128 v[216:219], v205 offset:7168
	global_load_lds_dwordx4 v[220:221], off
	v_lshl_add_u64 v[220:221], s[60:61], 0, v[174:175]
	s_add_i32 m0, s71, 0xe000
	s_nop 0
	global_load_lds_dwordx4 v[220:221], off
	s_waitcnt vmcnt(8)
	s_waitcnt lgkmcnt(0)
	s_barrier
	s_waitcnt lgkmcnt(0)
	v_mfma_f32_16x16x32_bf16 v[148:151], v[64:67], v[180:183], v[148:151]
	v_mfma_f32_16x16x32_bf16 v[144:147], v[72:75], v[180:183], v[144:147]
	v_mfma_f32_16x16x32_bf16 v[132:135], v[64:67], v[188:191], v[132:135]
	v_mfma_f32_16x16x32_bf16 v[128:131], v[72:75], v[188:191], v[128:131]
	v_mfma_f32_16x16x32_bf16 v[116:119], v[64:67], v[196:199], v[116:119]
	v_mfma_f32_16x16x32_bf16 v[112:115], v[72:75], v[196:199], v[112:115]
	v_mfma_f32_16x16x32_bf16 v[104:107], v[64:67], v[212:215], v[104:107]
	v_mfma_f32_16x16x32_bf16 v[100:103], v[72:75], v[212:215], v[100:103]
	v_mfma_f32_16x16x32_bf16 v[148:151], v[68:71], v[184:187], v[148:151]
	v_mfma_f32_16x16x32_bf16 v[144:147], v[76:79], v[184:187], v[144:147]
	v_mfma_f32_16x16x32_bf16 v[132:135], v[68:71], v[192:195], v[132:135]
	v_mfma_f32_16x16x32_bf16 v[128:131], v[76:79], v[192:195], v[128:131]
	v_mfma_f32_16x16x32_bf16 v[116:119], v[68:71], v[208:211], v[116:119]
	v_mfma_f32_16x16x32_bf16 v[112:115], v[76:79], v[208:211], v[112:115]
	v_mfma_f32_16x16x32_bf16 v[104:107], v[68:71], v[216:219], v[104:107]
	v_mfma_f32_16x16x32_bf16 v[100:103], v[76:79], v[216:219], v[100:103]
	v_mfma_f32_16x16x32_bf16 v[152:155], v[80:83], v[180:183], v[152:155]
	v_mfma_f32_16x16x32_bf16 v[156:159], v[88:91], v[180:183], v[156:159]
	v_mfma_f32_16x16x32_bf16 v[136:139], v[80:83], v[188:191], v[136:139]
	v_mfma_f32_16x16x32_bf16 v[140:143], v[88:91], v[188:191], v[140:143]
	v_mfma_f32_16x16x32_bf16 v[120:123], v[80:83], v[196:199], v[120:123]
	v_mfma_f32_16x16x32_bf16 v[124:127], v[88:91], v[196:199], v[124:127]
	v_mfma_f32_16x16x32_bf16 v[96:99], v[80:83], v[212:215], v[96:99]
	v_mfma_f32_16x16x32_bf16 v[108:111], v[88:91], v[212:215], v[108:111]
	v_mfma_f32_16x16x32_bf16 v[152:155], v[84:87], v[184:187], v[152:155]
	v_mfma_f32_16x16x32_bf16 v[156:159], v[92:95], v[184:187], v[156:159]
	v_mfma_f32_16x16x32_bf16 v[136:139], v[84:87], v[192:195], v[136:139]
	v_mfma_f32_16x16x32_bf16 v[140:143], v[92:95], v[192:195], v[140:143]
	v_mfma_f32_16x16x32_bf16 v[120:123], v[84:87], v[208:211], v[120:123]
	v_mfma_f32_16x16x32_bf16 v[124:127], v[92:95], v[208:211], v[124:127]
	v_mfma_f32_16x16x32_bf16 v[96:99], v[84:87], v[216:219], v[96:99]
	v_mfma_f32_16x16x32_bf16 v[108:111], v[92:95], v[216:219], v[108:111]
	s_barrier
	s_add_i32 s89, s80, s70
	v_lshl_add_u64 v[220:221], s[62:63], 0, v[164:165]
	s_mov_b32 m0, s89
	ds_read_b128 v[180:183], v205 offset:16384
	ds_read_b128 v[184:187], v205 offset:17408
	ds_read_b128 v[188:191], v205 offset:18432
	ds_read_b128 v[192:195], v205 offset:19456
	ds_read_b128 v[196:199], v205 offset:20480
	ds_read_b128 v[208:211], v205 offset:21504
	ds_read_b128 v[212:215], v205 offset:22528
	ds_read_b128 v[216:219], v205 offset:23552
	global_load_lds_dwordx4 v[220:221], off
	s_add_i32 m0, s89, 0x2000
	s_add_u32 s90, s62, 0x40000
	v_lshl_add_u64 v[222:223], s[62:63], 0, v[160:161]
	s_addc_u32 s91, s63, 0
	s_add_i32 s89, s81, s70
	global_load_lds_dwordx4 v[222:223], off
	v_lshl_add_u64 v[224:225], s[90:91], 0, v[164:165]
	s_mov_b32 m0, s89
	v_lshl_add_u64 v[226:227], s[64:65], 0, v[162:163]
	global_load_lds_dwordx4 v[224:225], off
	v_lshl_add_u64 v[224:225], s[90:91], 0, v[160:161]
	s_add_i32 m0, s89, 0x2000
	s_nop 0
	global_load_lds_dwordx4 v[224:225], off
	v_lshl_add_u64 v[224:225], s[64:65], 0, v[166:167]
	s_mov_b32 m0, s71
	s_nop 0
	global_load_lds_dwordx4 v[224:225], off
	s_mov_b32 m0, s72
	s_nop 0
	global_load_lds_dwordx4 v[226:227], off
	s_waitcnt vmcnt(8)
	s_waitcnt lgkmcnt(0)
	s_barrier
	s_waitcnt lgkmcnt(0)
	v_mfma_f32_16x16x32_bf16 v[52:55], v[64:67], v[180:183], v[52:55]
	v_mfma_f32_16x16x32_bf16 v[48:51], v[72:75], v[180:183], v[48:51]
	v_mfma_f32_16x16x32_bf16 v[36:39], v[64:67], v[188:191], v[36:39]
	v_mfma_f32_16x16x32_bf16 v[32:35], v[72:75], v[188:191], v[32:35]
	v_mfma_f32_16x16x32_bf16 v[20:23], v[64:67], v[196:199], v[20:23]
	v_mfma_f32_16x16x32_bf16 v[16:19], v[72:75], v[196:199], v[16:19]
	v_mfma_f32_16x16x32_bf16 v[8:11], v[64:67], v[212:215], v[8:11]
	v_mfma_f32_16x16x32_bf16 v[4:7], v[72:75], v[212:215], v[4:7]
	v_mfma_f32_16x16x32_bf16 v[52:55], v[68:71], v[184:187], v[52:55]
	v_mfma_f32_16x16x32_bf16 v[48:51], v[76:79], v[184:187], v[48:51]
	v_mfma_f32_16x16x32_bf16 v[36:39], v[68:71], v[192:195], v[36:39]
	v_mfma_f32_16x16x32_bf16 v[32:35], v[76:79], v[192:195], v[32:35]
	v_mfma_f32_16x16x32_bf16 v[20:23], v[68:71], v[208:211], v[20:23]
	v_mfma_f32_16x16x32_bf16 v[16:19], v[76:79], v[208:211], v[16:19]
	v_mfma_f32_16x16x32_bf16 v[8:11], v[68:71], v[216:219], v[8:11]
	v_mfma_f32_16x16x32_bf16 v[4:7], v[76:79], v[216:219], v[4:7]
	v_mfma_f32_16x16x32_bf16 v[56:59], v[80:83], v[180:183], v[56:59]
	v_mfma_f32_16x16x32_bf16 v[60:63], v[88:91], v[180:183], v[60:63]
	v_mfma_f32_16x16x32_bf16 v[40:43], v[80:83], v[188:191], v[40:43]
	v_mfma_f32_16x16x32_bf16 v[44:47], v[88:91], v[188:191], v[44:47]
	v_mfma_f32_16x16x32_bf16 v[24:27], v[80:83], v[196:199], v[24:27]
	v_mfma_f32_16x16x32_bf16 v[28:31], v[88:91], v[196:199], v[28:31]
	v_mfma_f32_16x16x32_bf16 v[0:3], v[80:83], v[212:215], v[0:3]
	v_mfma_f32_16x16x32_bf16 v[12:15], v[88:91], v[212:215], v[12:15]
	v_mfma_f32_16x16x32_bf16 v[56:59], v[84:87], v[184:187], v[56:59]
	v_mfma_f32_16x16x32_bf16 v[60:63], v[92:95], v[184:187], v[60:63]
	v_mfma_f32_16x16x32_bf16 v[40:43], v[84:87], v[192:195], v[40:43]
	v_mfma_f32_16x16x32_bf16 v[44:47], v[92:95], v[192:195], v[44:47]
	v_mfma_f32_16x16x32_bf16 v[24:27], v[84:87], v[208:211], v[24:27]
	v_mfma_f32_16x16x32_bf16 v[28:31], v[92:95], v[208:211], v[28:31]
	v_mfma_f32_16x16x32_bf16 v[0:3], v[84:87], v[216:219], v[0:3]
	v_mfma_f32_16x16x32_bf16 v[12:15], v[92:95], v[216:219], v[12:15]
	s_barrier
	s_add_i32 s89, 0, 0x18000
	s_add_i32 s90, 0, 0x1c000
	v_add_u32_e32 v76, s89, v201
	v_add_u32_e32 v92, s90, v201
	ds_read_b128 v[64:67], v76
	ds_read_b128 v[68:71], v76 offset:1024
	ds_read_b128 v[72:75], v76 offset:2048
	ds_read_b128 v[76:79], v76 offset:3072
	ds_read_b128 v[80:83], v92
	ds_read_b128 v[84:87], v92 offset:1024
	ds_read_b128 v[88:91], v92 offset:2048
	ds_read_b128 v[92:95], v92 offset:3072
	s_add_u32 s64, s64, 0x40000
	s_addc_u32 s65, s65, 0
	s_mov_b32 m0, s73
	v_lshl_add_u64 v[228:229], s[64:65], 0, v[166:167]
	ds_read_b128 v[180:183], v205 offset:32768
	ds_read_b128 v[184:187], v205 offset:33792
	ds_read_b128 v[188:191], v205 offset:34816
	ds_read_b128 v[192:195], v205 offset:35840
	ds_read_b128 v[196:199], v205 offset:36864
	ds_read_b128 v[208:211], v205 offset:37888
	ds_read_b128 v[212:215], v205 offset:38912
	ds_read_b128 v[216:219], v205 offset:39936
	global_load_lds_dwordx4 v[228:229], off
	v_lshl_add_u64 v[228:229], s[64:65], 0, v[162:163]
	s_mov_b32 m0, s74
	s_nop 0
	global_load_lds_dwordx4 v[228:229], off
	s_waitcnt vmcnt(8)
	s_waitcnt lgkmcnt(0)
	s_barrier
	s_waitcnt lgkmcnt(0)
	v_mfma_f32_16x16x32_bf16 v[148:151], v[64:67], v[180:183], v[148:151]
	v_mfma_f32_16x16x32_bf16 v[144:147], v[72:75], v[180:183], v[144:147]
	v_mfma_f32_16x16x32_bf16 v[132:135], v[64:67], v[188:191], v[132:135]
	v_mfma_f32_16x16x32_bf16 v[128:131], v[72:75], v[188:191], v[128:131]
	v_mfma_f32_16x16x32_bf16 v[116:119], v[64:67], v[196:199], v[116:119]
	v_mfma_f32_16x16x32_bf16 v[112:115], v[72:75], v[196:199], v[112:115]
	v_mfma_f32_16x16x32_bf16 v[104:107], v[64:67], v[212:215], v[104:107]
	v_mfma_f32_16x16x32_bf16 v[100:103], v[72:75], v[212:215], v[100:103]
	v_mfma_f32_16x16x32_bf16 v[148:151], v[68:71], v[184:187], v[148:151]
	v_mfma_f32_16x16x32_bf16 v[144:147], v[76:79], v[184:187], v[144:147]
	v_mfma_f32_16x16x32_bf16 v[132:135], v[68:71], v[192:195], v[132:135]
	v_mfma_f32_16x16x32_bf16 v[128:131], v[76:79], v[192:195], v[128:131]
	v_mfma_f32_16x16x32_bf16 v[116:119], v[68:71], v[208:211], v[116:119]
	v_mfma_f32_16x16x32_bf16 v[112:115], v[76:79], v[208:211], v[112:115]
	v_mfma_f32_16x16x32_bf16 v[104:107], v[68:71], v[216:219], v[104:107]
	v_mfma_f32_16x16x32_bf16 v[100:103], v[76:79], v[216:219], v[100:103]
	v_mfma_f32_16x16x32_bf16 v[152:155], v[80:83], v[180:183], v[152:155]
	v_mfma_f32_16x16x32_bf16 v[156:159], v[88:91], v[180:183], v[156:159]
	v_mfma_f32_16x16x32_bf16 v[136:139], v[80:83], v[188:191], v[136:139]
	v_mfma_f32_16x16x32_bf16 v[140:143], v[88:91], v[188:191], v[140:143]
	v_mfma_f32_16x16x32_bf16 v[120:123], v[80:83], v[196:199], v[120:123]
	v_mfma_f32_16x16x32_bf16 v[124:127], v[88:91], v[196:199], v[124:127]
	v_mfma_f32_16x16x32_bf16 v[96:99], v[80:83], v[212:215], v[96:99]
	v_mfma_f32_16x16x32_bf16 v[108:111], v[88:91], v[212:215], v[108:111]
	v_mfma_f32_16x16x32_bf16 v[152:155], v[84:87], v[184:187], v[152:155]
	v_mfma_f32_16x16x32_bf16 v[156:159], v[92:95], v[184:187], v[156:159]
	v_mfma_f32_16x16x32_bf16 v[136:139], v[84:87], v[192:195], v[136:139]
	v_mfma_f32_16x16x32_bf16 v[140:143], v[92:95], v[192:195], v[140:143]
	v_mfma_f32_16x16x32_bf16 v[120:123], v[84:87], v[208:211], v[120:123]
	v_mfma_f32_16x16x32_bf16 v[124:127], v[92:95], v[208:211], v[124:127]
	v_mfma_f32_16x16x32_bf16 v[96:99], v[84:87], v[216:219], v[96:99]
	v_mfma_f32_16x16x32_bf16 v[108:111], v[92:95], v[216:219], v[108:111]
	s_barrier
	s_add_i32 s64, s89, s70
	v_lshl_add_u64 v[220:221], v[220:221], 0, s[36:37]
	s_mov_b32 m0, s64
	ds_read_b128 v[180:183], v205 offset:49152
	ds_read_b128 v[184:187], v205 offset:50176
	ds_read_b128 v[188:191], v205 offset:51200
	ds_read_b128 v[192:195], v205 offset:52224
	ds_read_b128 v[196:199], v205 offset:53248
	ds_read_b128 v[208:211], v205 offset:54272
	ds_read_b128 v[212:215], v205 offset:55296
	ds_read_b128 v[216:219], v205 offset:56320
	global_load_lds_dwordx4 v[220:221], off
	s_add_i32 m0, s64, 0x2000
	s_add_u32 s62, s62, 0x40080
	v_lshl_add_u64 v[220:221], v[222:223], 0, s[36:37]
	s_addc_u32 s63, s63, 0
	s_add_i32 s64, s90, s70
	global_load_lds_dwordx4 v[220:221], off
	v_lshl_add_u64 v[220:221], s[62:63], 0, v[164:165]
	s_mov_b32 m0, s64
	s_nop 0
	global_load_lds_dwordx4 v[220:221], off
	v_lshl_add_u64 v[220:221], s[62:63], 0, v[160:161]
	s_add_i32 m0, s64, 0x2000
	s_nop 0
	global_load_lds_dwordx4 v[220:221], off
	v_lshl_add_u64 v[220:221], v[224:225], 0, s[36:37]
	s_mov_b32 m0, s76
	s_nop 0
	global_load_lds_dwordx4 v[220:221], off
	v_lshl_add_u64 v[220:221], v[226:227], 0, s[36:37]
	s_mov_b32 m0, s77
	s_nop 0
	global_load_lds_dwordx4 v[220:221], off
	s_waitcnt vmcnt(8)
	s_waitcnt lgkmcnt(0)
	s_barrier
	s_waitcnt lgkmcnt(0)
	v_mfma_f32_16x16x32_bf16 v[52:55], v[64:67], v[180:183], v[52:55]
	v_mfma_f32_16x16x32_bf16 v[48:51], v[72:75], v[180:183], v[48:51]
	v_mfma_f32_16x16x32_bf16 v[36:39], v[64:67], v[188:191], v[36:39]
	v_mfma_f32_16x16x32_bf16 v[32:35], v[72:75], v[188:191], v[32:35]
	v_mfma_f32_16x16x32_bf16 v[20:23], v[64:67], v[196:199], v[20:23]
	v_mfma_f32_16x16x32_bf16 v[16:19], v[72:75], v[196:199], v[16:19]
	v_mfma_f32_16x16x32_bf16 v[8:11], v[64:67], v[212:215], v[8:11]
	v_mfma_f32_16x16x32_bf16 v[4:7], v[72:75], v[212:215], v[4:7]
	v_mfma_f32_16x16x32_bf16 v[52:55], v[68:71], v[184:187], v[52:55]
	v_mfma_f32_16x16x32_bf16 v[48:51], v[76:79], v[184:187], v[48:51]
	v_mfma_f32_16x16x32_bf16 v[36:39], v[68:71], v[192:195], v[36:39]
	v_mfma_f32_16x16x32_bf16 v[32:35], v[76:79], v[192:195], v[32:35]
	v_mfma_f32_16x16x32_bf16 v[20:23], v[68:71], v[208:211], v[20:23]
	v_mfma_f32_16x16x32_bf16 v[16:19], v[76:79], v[208:211], v[16:19]
	v_mfma_f32_16x16x32_bf16 v[8:11], v[68:71], v[216:219], v[8:11]
	v_mfma_f32_16x16x32_bf16 v[4:7], v[76:79], v[216:219], v[4:7]
	v_mfma_f32_16x16x32_bf16 v[56:59], v[80:83], v[180:183], v[56:59]
	v_mfma_f32_16x16x32_bf16 v[60:63], v[88:91], v[180:183], v[60:63]
	v_mfma_f32_16x16x32_bf16 v[40:43], v[80:83], v[188:191], v[40:43]
	v_mfma_f32_16x16x32_bf16 v[44:47], v[88:91], v[188:191], v[44:47]
	v_mfma_f32_16x16x32_bf16 v[24:27], v[80:83], v[196:199], v[24:27]
	v_mfma_f32_16x16x32_bf16 v[28:31], v[88:91], v[196:199], v[28:31]
	v_mfma_f32_16x16x32_bf16 v[0:3], v[80:83], v[212:215], v[0:3]
	v_mfma_f32_16x16x32_bf16 v[12:15], v[88:91], v[212:215], v[12:15]
	v_mfma_f32_16x16x32_bf16 v[56:59], v[84:87], v[184:187], v[56:59]
	v_mfma_f32_16x16x32_bf16 v[60:63], v[92:95], v[184:187], v[60:63]
	v_mfma_f32_16x16x32_bf16 v[40:43], v[84:87], v[192:195], v[40:43]
	v_mfma_f32_16x16x32_bf16 v[44:47], v[92:95], v[192:195], v[44:47]
	v_mfma_f32_16x16x32_bf16 v[24:27], v[84:87], v[208:211], v[24:27]
	v_mfma_f32_16x16x32_bf16 v[28:31], v[92:95], v[208:211], v[28:31]
	v_mfma_f32_16x16x32_bf16 v[0:3], v[84:87], v[216:219], v[0:3]
	v_mfma_f32_16x16x32_bf16 v[12:15], v[92:95], v[216:219], v[12:15]
	s_barrier
	s_add_i32 s88, s88, 2
	s_add_u32 s60, s60, 0x100
	s_addc_u32 s61, s61, 0
	s_add_u32 s86, s86, 0x100
	s_addc_u32 s87, s87, 0
	s_cmp_gt_u32 s88, 13
	s_cbranch_scc0 .LBB0_1552
	s_setprio 0
	v_lshl_or_b32 v180, s1, 7, v202
	v_ashrrev_i32_e32 v181, 31, v180
	v_lshlrev_b64 v[190:191], 2, v[180:181]
	v_lshl_add_u64 v[68:69], s[12:13], 0, v[190:191]
	v_lshl_add_u64 v[70:71], s[44:45], 0, v[190:191]
	v_lshl_add_u64 v[72:73], s[50:51], 0, v[190:191]
	v_lshl_add_u64 v[84:85], s[14:15], 0, v[190:191]
	global_load_dwordx4 v[64:67], v[68:69], off
	global_load_dwordx4 v[80:83], v[68:69], off offset:16
	global_load_dwordx4 v[92:95], v[70:71], off offset:16
	global_load_dwordx4 v[76:79], v[70:71], off
	global_load_dwordx4 v[88:91], v[72:73], off offset:16
	s_nop 0
	global_load_dwordx4 v[72:75], v[72:73], off
	s_nop 0
	global_load_dwordx4 v[68:71], v[84:85], off
	s_nop 0
	global_load_dwordx4 v[84:87], v[84:85], off offset:16
	s_and_b64 vcc, exec, s[38:39]
	s_cbranch_vccz .LBB0_1555
	s_barrier
.LBB0_1555:
	s_lshl_b32 s1, s0, 2
	s_add_i32 s60, s1, s69
	s_ashr_i32 s61, s60, 31
	v_mov_b32_dpp v183, v148 row_ror:1 row_mask:0xf bank_mask:0xf
	v_mov_b32_dpp v209, v148 row_ror:2 row_mask:0xf bank_mask:0xf
	v_mov_b32_dpp v185, v149 row_ror:1 row_mask:0xf bank_mask:0xf
	v_mov_b32_dpp v210, v149 row_ror:2 row_mask:0xf bank_mask:0xf
	v_mov_b32_dpp v187, v150 row_ror:1 row_mask:0xf bank_mask:0xf
	v_mov_b32_dpp v211, v150 row_ror:2 row_mask:0xf bank_mask:0xf
	v_mov_b32_dpp v189, v151 row_ror:1 row_mask:0xf bank_mask:0xf
	v_mov_b32_dpp v212, v151 row_ror:2 row_mask:0xf bank_mask:0xf
	v_mov_b32_dpp v193, v144 row_ror:1 row_mask:0xf bank_mask:0xf
	v_mov_b32_dpp v213, v144 row_ror:2 row_mask:0xf bank_mask:0xf
	v_mov_b32_dpp v195, v145 row_ror:1 row_mask:0xf bank_mask:0xf
	v_mov_b32_dpp v192, v145 row_ror:2 row_mask:0xf bank_mask:0xf
	v_mov_b32_dpp v197, v146 row_ror:1 row_mask:0xf bank_mask:0xf
	v_mov_b32_dpp v194, v146 row_ror:2 row_mask:0xf bank_mask:0xf
	v_mov_b32_dpp v199, v147 row_ror:1 row_mask:0xf bank_mask:0xf
	v_mov_b32_dpp v196, v147 row_ror:2 row_mask:0xf bank_mask:0xf
	s_lshl_b64 s[62:63], s[60:61], 1
	v_mov_b32_dpp v183, v148 row_shr:1 row_mask:0xf bank_mask:0xf
	v_mov_b32_dpp v209, v148 row_shr:2 row_mask:0xf bank_mask:0xf
	v_mov_b32_dpp v185, v149 row_shr:1 row_mask:0xf bank_mask:0xf
	v_mov_b32_dpp v210, v149 row_shr:2 row_mask:0xf bank_mask:0xf
	v_mov_b32_dpp v187, v150 row_shr:1 row_mask:0xf bank_mask:0xf
	v_mov_b32_dpp v211, v150 row_shr:2 row_mask:0xf bank_mask:0xf
	v_mov_b32_dpp v189, v151 row_shr:1 row_mask:0xf bank_mask:0xf
	v_mov_b32_dpp v212, v151 row_shr:2 row_mask:0xf bank_mask:0xf
	v_mov_b32_dpp v193, v144 row_shr:1 row_mask:0xf bank_mask:0xf
	v_mov_b32_dpp v213, v144 row_shr:2 row_mask:0xf bank_mask:0xf
	v_mov_b32_dpp v195, v145 row_shr:1 row_mask:0xf bank_mask:0xf
	v_mov_b32_dpp v192, v145 row_shr:2 row_mask:0xf bank_mask:0xf
	v_mov_b32_dpp v197, v146 row_shr:1 row_mask:0xf bank_mask:0xf
	v_mov_b32_dpp v194, v146 row_shr:2 row_mask:0xf bank_mask:0xf
	v_mov_b32_dpp v199, v147 row_shr:1 row_mask:0xf bank_mask:0xf
	v_mov_b32_dpp v196, v147 row_shr:2 row_mask:0xf bank_mask:0xf
	s_and_saveexec_b64 s[64:65], s[2:3]
	s_xor_b64 s[64:65], exec, s[64:65]
	s_cbranch_execz .LBB0_1557
	v_or_b32_e32 v186, s62, v168
	v_mov_b64_e32 v[182:183], s[20:21]
	v_mov_b64_e32 v[184:185], s[34:35]
	v_mad_u64_u32 v[182:183], s[84:85], v186, s82, v[182:183]
	v_mad_u64_u32 v[184:185], s[84:85], v186, s82, v[184:185]
	v_mad_i32_i24 v183, s63, v207, v183
	v_mad_i32_i24 v185, s63, v207, v185
	v_lshl_add_u64 v[182:183], v[182:183], 0, v[190:191]
	v_lshl_add_u64 v[184:185], v[184:185], 0, v[190:191]
	global_store_dwordx4 v[182:183], v[148:151], off
	global_store_dwordx4 v[182:183], v[144:147], off offset:16
	global_store_dwordx4 v[184:185], v[152:155], off
	global_store_dwordx4 v[184:185], v[156:159], off offset:16
	s_waitcnt vmcnt(0)
	v_mov_b32_e32 v188, v91
	v_mov_b32_e32 v186, v89
	v_mov_b32_e32 v184, v75
	v_mov_b32_e32 v182, v73
